# kernel start: grid-sync word sampled by wave 1 at the head of the S5 item's store stage; behind the item only the sample is waited for (vmcnt(8)) and the wait is skipped when the sync is complete
# speedup vs baseline: 1.0006x; 1.0006x over previous
.Lssa_490:
	s_or_b64 exec, exec, s[4:5]
	s_waitcnt vmcnt(0)
	v_add_f32_e32 v4, v5, v6
	s_lshl_b32 s86, s97, 6
	s_lshl_b32 s87, s82, 8
	s_mov_b32 s91, 0
	ds_write_b32 v69, v4 offset:25116
	s_waitcnt lgkmcnt(0)
	s_barrier
	s_mov_b32 s98, 0
	v_readfirstlane_b32 s4, v208
	s_cmp_eq_u32 s4, 64
	s_cbranch_scc0 .Lbt3_nocg
	v_mov_b32_e32 v15, 0
	global_load_dword v14, v15, s[100:101] offset:32 sc1
	s_mov_b32 s98, 2
.Lbt3_nocg:
	s_branch .Lssa_493

.Lssa_exit:
	s_mov_b32 s100, 0
	v_readfirstlane_b32 s79, v208
	v_cmp_gt_u32_e64 s[4:5], 32, v208
	v_cmp_eq_u32_e32 vcc, 64, v208
	s_and_saveexec_b64 s[6:7], vcc
	s_cbranch_execz .LBB0_24
	s_cmp_eq_u32 s98, 2
	s_cbranch_scc0 .Lcg_orig
	s_waitcnt vmcnt(8)
	v_and_b32_e32 v14, 0xffff0000, v14
	s_nop 0
	v_readfirstlane_b32 s98, v14
	s_cmp_lg_u32 s98, s99
	s_cbranch_scc1 .LBB0_23
.Lcg_orig:
	s_load_dwordx2 s[8:9], s[0:1], 0x110
	v_mov_b32_e32 v0, 0
	v_mov_b32_e32 v1, s99
	s_waitcnt lgkmcnt(0)
	global_load_dword v2, v0, s[8:9] offset:32 sc1
	s_waitcnt vmcnt(0)
	v_and_b32_e32 v2, 0xffff0000, v2
	v_cmp_eq_u32_e32 vcc, v2, v1
	s_and_b64 exec, exec, vcc
	s_cbranch_execz .LBB0_23
	s_mov_b64 s[10:11], 0
